# layer-1 weight-transpose filler tiles: four row loads issued together instead of load-wait-stage one by one
# speedup vs baseline: 1.0046x; 1.0046x over previous
; DI void wt_tile(const Params& p, int l, int idx, unsigned char* smem, int tid) {
;     ...
;   __syncthreads();
; #pragma unroll
;   for (int m = 0; m < 4; ++m) {
;     const int e = tid + 256 * m;
;     const int i = e >> 4, j4 = e & 15;
;     const int n = nt * 64 + j4 * 4;
;     float4 v = make_float4(0.f, 0.f, 0.f, 0.f);
;     if (n < Nsrc) v = *(const float4*)(src + (size_t)(kt * 64 + i) * Nsrc + n);
;     tile[i * 65 + j4 * 4 + 0] = v.x; tile[i * 65 + j4 * 4 + 1] = v.y; tile[i * 65 + j4 * 4 + 2] = v.z; tile[i * 65 + j4 * 4 + 3] = v.w;
;   }
.LBB0_572:
	s_or_saveexec_b64 s[4:5], s[4:5]
	s_lshl_b32 s8, s8, 6
	v_mov_b32_e32 v4, 0
	v_mov_b32_e32 v5, 0
	v_mov_b32_e32 v6, 0
	v_mov_b32_e32 v7, 0
	v_mov_b32_e32 v0, 0
	v_mov_b32_e32 v1, 0
	v_mov_b32_e32 v2, 0
	v_mov_b32_e32 v3, 0
	s_xor_b64 exec, exec, s[4:5]
	s_cbranch_execz .LBB0_569
	v_readlane_b32 s72, v253, 7
	v_readlane_b32 s76, v253, 11
	v_readlane_b32 s77, v253, 12
	v_readlane_b32 s78, v253, 13
	v_readlane_b32 s79, v253, 14
	v_readlane_b32 s84, v253, 19
	v_readlane_b32 s85, v253, 20
	v_readlane_b32 s80, v253, 15
	v_readlane_b32 s81, v253, 16
	v_readlane_b32 s82, v253, 17
	v_readlane_b32 s83, v253, 18
	v_readlane_b32 s86, v253, 21
	v_readlane_b32 s87, v253, 22
	s_mov_b64 s[76:77], s[84:85]
	s_mov_b64 s[78:79], s[86:87]
	v_readlane_b32 s80, v253, 23
	s_and_b64 s[10:11], s[0:1], exec
	v_readlane_b32 s94, v253, 37
	s_mov_b32 s12, 0x1110000
	v_readlane_b32 s95, v253, 38
	s_cselect_b32 s10, s78, s94
	s_cselect_b32 s12, s12, 0x400000
	s_cselect_b32 s11, s79, s95
	s_add_u32 s10, s10, s12
	s_addc_u32 s11, s11, 0
	v_ashrrev_i32_e32 v9, 31, v8
	v_add_u32_e32 v0, s8, v11
	v_lshl_add_u64 v[4:5], v[8:9], 2, s[10:11]
	v_mad_i64_i32 v[0:1], s[10:11], v0, s9, 0
	v_add_u32_e32 v2, s8, v12
	v_lshl_add_u64 v[0:1], v[0:1], 2, v[4:5]
	v_mad_i64_i32 v[2:3], s[10:11], v2, s9, 0
	v_lshl_add_u64 v[6:7], v[2:3], 2, v[4:5]
	v_add_u32_e32 v32, s8, v13
	v_mad_i64_i32 v[32:33], s[10:11], v32, s9, 0
	v_lshl_add_u64 v[32:33], v[32:33], 2, v[4:5]
	v_add_u32_e32 v34, s8, v14
	v_mad_i64_i32 v[34:35], s[10:11], v34, s9, 0
	v_lshl_add_u64 v[34:35], v[34:35], 2, v[4:5]
	global_load_dwordx4 v[36:39], v[0:1], off
	global_load_dwordx4 v[40:43], v[6:7], off
	global_load_dwordx4 v[0:3], v[32:33], off
	s_nop 0
	global_load_dwordx4 v[4:7], v[34:35], off
	v_readlane_b32 s73, v253, 8
	v_readlane_b32 s72, v254, 15
	v_readlane_b32 s68, v254, 21
	v_readlane_b32 s73, v254, 16
	v_readlane_b32 s69, v254, 22
	v_readlane_b32 s74, v253, 9
	v_readlane_b32 s75, v253, 10
	v_readlane_b32 s81, v253, 24
	v_readlane_b32 s82, v253, 25
	v_readlane_b32 s83, v253, 26
	v_readlane_b32 s84, v253, 27
	v_readlane_b32 s85, v253, 28
	v_readlane_b32 s86, v253, 29
	v_readlane_b32 s87, v253, 30
	v_readlane_b32 s88, v253, 31
	v_readlane_b32 s89, v253, 32
	v_readlane_b32 s90, v253, 33
	v_readlane_b32 s91, v253, 34
	v_readlane_b32 s92, v253, 35
	v_readlane_b32 s93, v253, 36
	s_waitcnt vmcnt(2)
	ds_write2_b32 v22, v36, v37 offset1:1
	ds_write2_b32 v22, v38, v39 offset0:2 offset1:3
	ds_write2_b32 v23, v40, v41 offset1:1
	ds_write2_b32 v23, v42, v43 offset0:2 offset1:3
	s_branch .LBB0_569
